# residual-gate epilogue: leading half issues its 20 epilogue loads before the alignment barrier (they stream during the wait)
# baseline (speedup 1.0000x reference)
; #define PG8_STAGE(bufoff, gbase, voff) do { _Pragma("unroll") for (int _i = 0; _i < 2; ++_i) \
;         __builtin_amdgcn_global_load_lds((const unsigned*)((const char*)(gbase) + (voff)[_i]), (PG8_LAS unsigned*)(lds + (bufoff) + ldsw + _i * 8192), 16, 0, 0); } while (0)
; #define PG8_LDA(dst, b, h) do { _Pragma("unroll") for (int m = 0; m < 4; ++m) _Pragma("unroll") for (int k = 0; k < 2; ++k) dst[m][k] = *(const PG8_LAS bf16x8*)(lds + PG8_SA(b, h) + aoff + m * 2048 + k * 1024); } while (0)
; #define PG8_LDB(dst, b, h) do { _Pragma("unroll") for (int n = 0; n < 2; ++n) _Pragma("unroll") for (int k = 0; k < 2; ++k) dst[n][k] = *(const PG8_LAS bf16x8*)(lds + PG8_SB(b, h) + boff + n * 2048 + k * 1024); } while (0)
; #define PG8_MMA(ai, bj, At, Bt) do { __builtin_amdgcn_s_setprio(1); _Pragma("unroll") for (int m = 0; m < 4; ++m) _Pragma("unroll") for (int n = 0; n < 2; ++n) _Pragma("unroll") for (int k = 0; k < 2; ++k) \
;         acc[ai][bj][m][n] = __builtin_amdgcn_mfma_f32_16x16x32_bf16(Bt[n][k], At[m][k], acc[ai][bj][m][n], 0, 0, 0); __builtin_amdgcn_s_setprio(0); } while (0)
; #define PG8_WAIT_V(n) asm volatile("s_waitcnt vmcnt(" #n ")" ::: "memory")
; template <class Epi, class Sched, bool ALIGN_EPI = false, bool SP2 = false>
; __device__ __forceinline__ void gemm_phase(PG8_LAS unsigned char* lds, const Gemm g, const Sched& S, const Epi& E) {
;     ...
;             PG8_LDB(B0, 0, 0); PG8_LDB(B1, 0, 1); PG8_SCHED; PG8_LDA(At, 0, 0); PG8_STAGE(PG8_SA(1, 1), a1 + hstep, voffA);
;             PG8_WAIT_V(8); PG8_WAIT_L(0); PG8_BAR; PG8_MMA(0, 0, At, B0); PG8_MMA(0, 1, At, B1); PG8_BAR; PG8_SCHED;
;             PG8_LDA(At, 0, 1); PG8_STAGE(PG8_SB(0, 0), b2, voffB); PG8_STAGE(PG8_SB(0, 1), b2 + hstep, voffB); PG8_STAGE(PG8_SA(0, 0), a2, voffA);
;             PG8_WAIT_V(8); PG8_WAIT_L(0); PG8_BAR; PG8_MMA(1, 0, At, B0); PG8_MMA(1, 1, At, B1); PG8_BAR; PG8_SCHED;
;             PG8_LDB(B0, 1, 0); PG8_LDB(B1, 1, 1); PG8_SCHED; PG8_LDA(At, 1, 0); PG8_STAGE(PG8_SA(0, 1), a2 + hstep, voffA);
;             PG8_WAIT_V(8); PG8_WAIT_L(0); PG8_BAR; PG8_MMA(0, 0, At, B0); PG8_MMA(0, 1, At, B1); PG8_BAR; PG8_SCHED;
;             PG8_LDA(At, 1, 1); PG8_STAGE(PG8_SB(1, 0), b3, voffB); PG8_STAGE(PG8_SB(1, 1), b3 + hstep, voffB); PG8_STAGE(PG8_SA(1, 0), a3, voffA);
;             PG8_WAIT_V(8); PG8_WAIT_L(0); PG8_BAR; PG8_MMA(1, 0, At, B0); PG8_MMA(1, 1, At, B1); PG8_BAR; PG8_SCHED;
.LBB0_179:
	s_add_i32 s52, s26, 2
	s_add_u32 s54, s24, 0x80
	s_addc_u32 s27, s25, 0
	s_add_i32 s57, 0, 0x10000
	s_cmp_eq_u32 s42, s26
	s_cselect_b32 s27, s9, s27
	s_cselect_b32 s26, s8, s54
	s_cselect_b32 s55, s23, s51
	s_cselect_b32 s54, s22, s47
	s_add_i32 s58, 0, 0x14000
	v_add_u32_e32 v134, s57, v167
	v_add_u32_e32 v162, s58, v167
	ds_read_b128 v[106:109], v134
	ds_read_b128 v[110:113], v134 offset:1024
	ds_read_b128 v[130:133], v134 offset:2048
	ds_read_b128 v[134:137], v134 offset:3072
	ds_read_b128 v[158:161], v162
	ds_read_b128 v[170:173], v162 offset:1024
	ds_read_b128 v[174:177], v162 offset:2048
	ds_read_b128 v[178:181], v162 offset:3072
	v_lshl_add_u64 v[162:163], s[24:25], 0, v[154:155]
	s_add_i32 m0, s30, 0xc000
	ds_read_b128 v[182:185], v169
	ds_read_b128 v[186:189], v169 offset:1024
	ds_read_b128 v[190:193], v169 offset:2048
	ds_read_b128 v[194:197], v169 offset:3072
	ds_read_b128 v[198:201], v169 offset:4096
	ds_read_b128 v[202:205], v169 offset:5120
	ds_read_b128 v[206:209], v169 offset:6144
	ds_read_b128 v[210:213], v169 offset:7168
	global_load_lds_dwordx4 v[162:163], off
	v_lshl_add_u64 v[162:163], s[24:25], 0, v[156:157]
	s_add_i32 m0, s30, 0xe000
	s_nop 0
	global_load_lds_dwordx4 v[162:163], off
	s_waitcnt vmcnt(8)
	s_waitcnt lgkmcnt(0)
	s_barrier
	s_setprio 1
	s_waitcnt lgkmcnt(0)
	v_mfma_f32_16x16x32_bf16 v[142:145], v[106:109], v[182:185], v[142:145]
	v_mfma_f32_16x16x32_bf16 v[138:141], v[130:133], v[182:185], v[138:141]
	v_mfma_f32_16x16x32_bf16 v[118:121], v[106:109], v[190:193], v[118:121]
	v_mfma_f32_16x16x32_bf16 v[114:117], v[130:133], v[190:193], v[114:117]
	v_mfma_f32_16x16x32_bf16 v[94:97], v[106:109], v[198:201], v[94:97]
	v_mfma_f32_16x16x32_bf16 v[90:93], v[130:133], v[198:201], v[90:93]
	v_mfma_f32_16x16x32_bf16 v[78:81], v[106:109], v[206:209], v[78:81]
	v_mfma_f32_16x16x32_bf16 v[74:77], v[130:133], v[206:209], v[74:77]
	v_mfma_f32_16x16x32_bf16 v[142:145], v[110:113], v[186:189], v[142:145]
	v_mfma_f32_16x16x32_bf16 v[138:141], v[134:137], v[186:189], v[138:141]
	v_mfma_f32_16x16x32_bf16 v[118:121], v[110:113], v[194:197], v[118:121]
	v_mfma_f32_16x16x32_bf16 v[114:117], v[134:137], v[194:197], v[114:117]
	v_mfma_f32_16x16x32_bf16 v[94:97], v[110:113], v[202:205], v[94:97]
	v_mfma_f32_16x16x32_bf16 v[90:93], v[134:137], v[202:205], v[90:93]
	v_mfma_f32_16x16x32_bf16 v[78:81], v[110:113], v[210:213], v[78:81]
	v_mfma_f32_16x16x32_bf16 v[74:77], v[134:137], v[210:213], v[74:77]
	s_setprio 0
	s_setprio 1
	v_mfma_f32_16x16x32_bf16 v[126:129], v[158:161], v[182:185], v[126:129]
	v_mfma_f32_16x16x32_bf16 v[122:125], v[174:177], v[182:185], v[122:125]
	v_mfma_f32_16x16x32_bf16 v[102:105], v[158:161], v[190:193], v[102:105]
	v_mfma_f32_16x16x32_bf16 v[98:101], v[174:177], v[190:193], v[98:101]
	v_mfma_f32_16x16x32_bf16 v[86:89], v[158:161], v[198:201], v[86:89]
	v_mfma_f32_16x16x32_bf16 v[82:85], v[174:177], v[198:201], v[82:85]
	v_mfma_f32_16x16x32_bf16 v[70:73], v[158:161], v[206:209], v[70:73]
	v_mfma_f32_16x16x32_bf16 v[66:69], v[174:177], v[206:209], v[66:69]
	v_mfma_f32_16x16x32_bf16 v[126:129], v[170:173], v[186:189], v[126:129]
	v_mfma_f32_16x16x32_bf16 v[122:125], v[178:181], v[186:189], v[122:125]
	v_mfma_f32_16x16x32_bf16 v[102:105], v[170:173], v[194:197], v[102:105]
	v_mfma_f32_16x16x32_bf16 v[98:101], v[178:181], v[194:197], v[98:101]
	v_mfma_f32_16x16x32_bf16 v[86:89], v[170:173], v[202:205], v[86:89]
	v_mfma_f32_16x16x32_bf16 v[82:85], v[178:181], v[202:205], v[82:85]
	v_mfma_f32_16x16x32_bf16 v[70:73], v[170:173], v[210:213], v[70:73]
	v_mfma_f32_16x16x32_bf16 v[66:69], v[178:181], v[210:213], v[66:69]
	s_setprio 0
	s_barrier
	s_add_i32 s57, s57, s29
	v_lshl_add_u64 v[162:163], s[54:55], 0, v[150:151]
	s_mov_b32 m0, s57
	ds_read_b128 v[182:185], v169 offset:16384
	ds_read_b128 v[186:189], v169 offset:17408
	ds_read_b128 v[190:193], v169 offset:18432
	ds_read_b128 v[194:197], v169 offset:19456
	ds_read_b128 v[198:201], v169 offset:20480
	ds_read_b128 v[202:205], v169 offset:21504
	ds_read_b128 v[206:209], v169 offset:22528
	ds_read_b128 v[210:213], v169 offset:23552
	global_load_lds_dwordx4 v[162:163], off
	s_add_i32 m0, s57, 0x2000
	v_lshl_add_u64 v[218:219], s[54:55], 0, v[146:147]
	s_add_u32 s54, s54, s90
	s_addc_u32 s55, s55, 0
	s_add_i32 s57, s58, s29
	global_load_lds_dwordx4 v[218:219], off
	v_lshl_add_u64 v[220:221], s[54:55], 0, v[150:151]
	s_mov_b32 m0, s57
	v_lshl_add_u64 v[226:227], s[54:55], 0, v[146:147]
	global_load_lds_dwordx4 v[220:221], off
	s_add_i32 m0, s57, 0x2000
	v_lshl_add_u64 v[228:229], s[26:27], 0, v[152:153]
	global_load_lds_dwordx4 v[226:227], off
	s_mov_b32 m0, s30
	v_lshl_add_u64 v[230:231], s[26:27], 0, v[148:149]
	global_load_lds_dwordx4 v[228:229], off
	s_mov_b32 m0, s31
	s_nop 0
	global_load_lds_dwordx4 v[230:231], off
	s_waitcnt vmcnt(8)
	s_waitcnt lgkmcnt(0)
	s_barrier
; #define PG8_STAGE(bufoff, gbase, voff) do { _Pragma("unroll") for (int _i = 0; _i < 2; ++_i) \
;         __builtin_amdgcn_global_load_lds((const unsigned*)((const char*)(gbase) + (voff)[_i]), (PG8_LAS unsigned*)(lds + (bufoff) + ldsw + _i * 8192), 16, 0, 0); } while (0)
; #define PG8_LDA(dst, b, h) do { _Pragma("unroll") for (int m = 0; m < 4; ++m) _Pragma("unroll") for (int k = 0; k < 2; ++k) dst[m][k] = *(const PG8_LAS bf16x8*)(lds + PG8_SA(b, h) + aoff + m * 2048 + k * 1024); } while (0)
; #define PG8_LDB(dst, b, h) do { _Pragma("unroll") for (int n = 0; n < 2; ++n) _Pragma("unroll") for (int k = 0; k < 2; ++k) dst[n][k] = *(const PG8_LAS bf16x8*)(lds + PG8_SB(b, h) + boff + n * 2048 + k * 1024); } while (0)
; #define PG8_MMA(ai, bj, At, Bt) do { __builtin_amdgcn_s_setprio(1); _Pragma("unroll") for (int m = 0; m < 4; ++m) _Pragma("unroll") for (int n = 0; n < 2; ++n) _Pragma("unroll") for (int k = 0; k < 2; ++k) \
;         acc[ai][bj][m][n] = __builtin_amdgcn_mfma_f32_16x16x32_bf16(Bt[n][k], At[m][k], acc[ai][bj][m][n], 0, 0, 0); __builtin_amdgcn_s_setprio(0); } while (0)
; #define PG8_WAIT_V(n) asm volatile("s_waitcnt vmcnt(" #n ")" ::: "memory")
; template <class Epi, class Sched, bool ALIGN_EPI = false, bool SP2 = false>
; __device__ __forceinline__ void gemm_phase(PG8_LAS unsigned char* lds, const Gemm g, const Sched& S, const Epi& E) {
;     ...
;             PG8_LDB(B0, 0, 0); PG8_LDB(B1, 0, 1); PG8_SCHED; PG8_LDA(At, 0, 0); PG8_STAGE(PG8_SA(1, 1), a1 + hstep, voffA);
;             PG8_WAIT_V(8); PG8_WAIT_L(0); PG8_BAR; PG8_MMA(0, 0, At, B0); PG8_MMA(0, 1, At, B1); PG8_BAR; PG8_SCHED;
;             PG8_LDA(At, 0, 1); PG8_STAGE(PG8_SB(0, 0), b2, voffB); PG8_STAGE(PG8_SB(0, 1), b2 + hstep, voffB); PG8_STAGE(PG8_SA(0, 0), a2, voffA);
;             PG8_WAIT_V(8); PG8_WAIT_L(0); PG8_BAR; PG8_MMA(1, 0, At, B0); PG8_MMA(1, 1, At, B1); PG8_BAR; PG8_SCHED;
;             PG8_LDB(B0, 1, 0); PG8_LDB(B1, 1, 1); PG8_SCHED; PG8_LDA(At, 1, 0); PG8_STAGE(PG8_SA(0, 1), a2 + hstep, voffA);
;             PG8_WAIT_V(8); PG8_WAIT_L(0); PG8_BAR; PG8_MMA(0, 0, At, B0); PG8_MMA(0, 1, At, B1); PG8_BAR; PG8_SCHED;
;             PG8_LDA(At, 1, 1); PG8_STAGE(PG8_SB(1, 0), b3, voffB); PG8_STAGE(PG8_SB(1, 1), b3 + hstep, voffB); PG8_STAGE(PG8_SA(1, 0), a3, voffA);
;             PG8_WAIT_V(8); PG8_WAIT_L(0); PG8_BAR; PG8_MMA(1, 0, At, B0); PG8_MMA(1, 1, At, B1); PG8_BAR; PG8_SCHED;
	s_setprio 1
	s_waitcnt lgkmcnt(0)
	v_mfma_f32_16x16x32_bf16 v[62:65], v[106:109], v[182:185], v[62:65]
	v_mfma_f32_16x16x32_bf16 v[58:61], v[130:133], v[182:185], v[58:61]
	v_mfma_f32_16x16x32_bf16 v[46:49], v[106:109], v[190:193], v[46:49]
	v_mfma_f32_16x16x32_bf16 v[42:45], v[130:133], v[190:193], v[42:45]
	v_mfma_f32_16x16x32_bf16 v[30:33], v[106:109], v[198:201], v[30:33]
	v_mfma_f32_16x16x32_bf16 v[26:29], v[130:133], v[198:201], v[26:29]
	v_mfma_f32_16x16x32_bf16 v[14:17], v[106:109], v[206:209], v[14:17]
	v_mfma_f32_16x16x32_bf16 v[10:13], v[130:133], v[206:209], v[10:13]
	v_mfma_f32_16x16x32_bf16 v[62:65], v[110:113], v[186:189], v[62:65]
	v_mfma_f32_16x16x32_bf16 v[58:61], v[134:137], v[186:189], v[58:61]
	v_mfma_f32_16x16x32_bf16 v[46:49], v[110:113], v[194:197], v[46:49]
	v_mfma_f32_16x16x32_bf16 v[42:45], v[134:137], v[194:197], v[42:45]
	v_mfma_f32_16x16x32_bf16 v[30:33], v[110:113], v[202:205], v[30:33]
	v_mfma_f32_16x16x32_bf16 v[26:29], v[134:137], v[202:205], v[26:29]
	v_mfma_f32_16x16x32_bf16 v[14:17], v[110:113], v[210:213], v[14:17]
	v_mfma_f32_16x16x32_bf16 v[10:13], v[134:137], v[210:213], v[10:13]
	s_setprio 0
	s_setprio 1
	v_mfma_f32_16x16x32_bf16 v[54:57], v[158:161], v[182:185], v[54:57]
	v_mfma_f32_16x16x32_bf16 v[50:53], v[174:177], v[182:185], v[50:53]
	v_mfma_f32_16x16x32_bf16 v[38:41], v[158:161], v[190:193], v[38:41]
	v_mfma_f32_16x16x32_bf16 v[34:37], v[174:177], v[190:193], v[34:37]
	v_mfma_f32_16x16x32_bf16 v[22:25], v[158:161], v[198:201], v[22:25]
	v_mfma_f32_16x16x32_bf16 v[18:21], v[174:177], v[198:201], v[18:21]
	v_mfma_f32_16x16x32_bf16 v[6:9], v[158:161], v[206:209], v[6:9]
	v_mfma_f32_16x16x32_bf16 v[2:5], v[174:177], v[206:209], v[2:5]
	v_mfma_f32_16x16x32_bf16 v[54:57], v[170:173], v[186:189], v[54:57]
	v_mfma_f32_16x16x32_bf16 v[50:53], v[178:181], v[186:189], v[50:53]
	v_mfma_f32_16x16x32_bf16 v[38:41], v[170:173], v[194:197], v[38:41]
	v_mfma_f32_16x16x32_bf16 v[34:37], v[178:181], v[194:197], v[34:37]
	v_mfma_f32_16x16x32_bf16 v[22:25], v[170:173], v[202:205], v[22:25]
	v_mfma_f32_16x16x32_bf16 v[18:21], v[178:181], v[202:205], v[18:21]
	v_mfma_f32_16x16x32_bf16 v[6:9], v[170:173], v[210:213], v[6:9]
	v_mfma_f32_16x16x32_bf16 v[2:5], v[178:181], v[210:213], v[2:5]
	s_setprio 0
	s_barrier
	s_add_i32 s54, 0, 0x18000
	s_add_i32 s55, 0, 0x1c000
	v_add_u32_e32 v134, s54, v167
	v_add_u32_e32 v178, s55, v167
	ds_read_b128 v[106:109], v134
	ds_read_b128 v[110:113], v134 offset:1024
	ds_read_b128 v[130:133], v134 offset:2048
	ds_read_b128 v[134:137], v134 offset:3072
	ds_read_b128 v[158:161], v178
	ds_read_b128 v[170:173], v178 offset:1024
	ds_read_b128 v[174:177], v178 offset:2048
	ds_read_b128 v[178:181], v178 offset:3072
	s_add_u32 s26, s26, s90
	s_addc_u32 s27, s27, 0
	s_mov_b32 m0, s34
	v_lshl_add_u64 v[232:233], s[26:27], 0, v[152:153]
	ds_read_b128 v[182:185], v169 offset:32768
	ds_read_b128 v[186:189], v169 offset:33792
	ds_read_b128 v[190:193], v169 offset:34816
	ds_read_b128 v[194:197], v169 offset:35840
	ds_read_b128 v[198:201], v169 offset:36864
	ds_read_b128 v[202:205], v169 offset:37888
	ds_read_b128 v[206:209], v169 offset:38912
	ds_read_b128 v[210:213], v169 offset:39936
	global_load_lds_dwordx4 v[232:233], off
	v_lshl_add_u64 v[232:233], s[26:27], 0, v[148:149]
	s_mov_b32 m0, s35
	s_nop 0
	global_load_lds_dwordx4 v[232:233], off
	s_waitcnt vmcnt(8)
	s_waitcnt lgkmcnt(0)
	s_barrier
	s_setprio 1
	s_waitcnt lgkmcnt(0)
	v_mfma_f32_16x16x32_bf16 v[142:145], v[106:109], v[182:185], v[142:145]
	v_mfma_f32_16x16x32_bf16 v[138:141], v[130:133], v[182:185], v[138:141]
	v_mfma_f32_16x16x32_bf16 v[118:121], v[106:109], v[190:193], v[118:121]
	v_mfma_f32_16x16x32_bf16 v[114:117], v[130:133], v[190:193], v[114:117]
	v_mfma_f32_16x16x32_bf16 v[94:97], v[106:109], v[198:201], v[94:97]
	v_mfma_f32_16x16x32_bf16 v[90:93], v[130:133], v[198:201], v[90:93]
	v_mfma_f32_16x16x32_bf16 v[78:81], v[106:109], v[206:209], v[78:81]
	v_mfma_f32_16x16x32_bf16 v[74:77], v[130:133], v[206:209], v[74:77]
	v_mfma_f32_16x16x32_bf16 v[142:145], v[110:113], v[186:189], v[142:145]
	v_mfma_f32_16x16x32_bf16 v[138:141], v[134:137], v[186:189], v[138:141]
	v_mfma_f32_16x16x32_bf16 v[118:121], v[110:113], v[194:197], v[118:121]
	v_mfma_f32_16x16x32_bf16 v[114:117], v[134:137], v[194:197], v[114:117]
	v_mfma_f32_16x16x32_bf16 v[94:97], v[110:113], v[202:205], v[94:97]
	v_mfma_f32_16x16x32_bf16 v[90:93], v[134:137], v[202:205], v[90:93]
	v_mfma_f32_16x16x32_bf16 v[78:81], v[110:113], v[210:213], v[78:81]
	v_mfma_f32_16x16x32_bf16 v[74:77], v[134:137], v[210:213], v[74:77]
	s_setprio 0
	s_setprio 1
	v_mfma_f32_16x16x32_bf16 v[126:129], v[158:161], v[182:185], v[126:129]
	v_mfma_f32_16x16x32_bf16 v[122:125], v[174:177], v[182:185], v[122:125]
	v_mfma_f32_16x16x32_bf16 v[102:105], v[158:161], v[190:193], v[102:105]
	v_mfma_f32_16x16x32_bf16 v[98:101], v[174:177], v[190:193], v[98:101]
	v_mfma_f32_16x16x32_bf16 v[86:89], v[158:161], v[198:201], v[86:89]
	v_mfma_f32_16x16x32_bf16 v[82:85], v[174:177], v[198:201], v[82:85]
	v_mfma_f32_16x16x32_bf16 v[70:73], v[158:161], v[206:209], v[70:73]
	v_mfma_f32_16x16x32_bf16 v[66:69], v[174:177], v[206:209], v[66:69]
	v_mfma_f32_16x16x32_bf16 v[126:129], v[170:173], v[186:189], v[126:129]
	v_mfma_f32_16x16x32_bf16 v[122:125], v[178:181], v[186:189], v[122:125]
	v_mfma_f32_16x16x32_bf16 v[102:105], v[170:173], v[194:197], v[102:105]
	v_mfma_f32_16x16x32_bf16 v[98:101], v[178:181], v[194:197], v[98:101]
	v_mfma_f32_16x16x32_bf16 v[86:89], v[170:173], v[202:205], v[86:89]
	v_mfma_f32_16x16x32_bf16 v[82:85], v[178:181], v[202:205], v[82:85]
	v_mfma_f32_16x16x32_bf16 v[70:73], v[170:173], v[210:213], v[70:73]
	v_mfma_f32_16x16x32_bf16 v[66:69], v[178:181], v[210:213], v[66:69]
	s_setprio 0
	s_barrier
; #define PG8_STAGE(bufoff, gbase, voff) do { _Pragma("unroll") for (int _i = 0; _i < 2; ++_i) \
;         __builtin_amdgcn_global_load_lds((const unsigned*)((const char*)(gbase) + (voff)[_i]), (PG8_LAS unsigned*)(lds + (bufoff) + ldsw + _i * 8192), 16, 0, 0); } while (0)
; template <class Epi, class Sched, bool ALIGN_EPI = false, bool SP2 = false>
; __device__ __forceinline__ void gemm_phase(PG8_LAS unsigned char* lds, const Gemm g, const Sched& S, const Epi& E) {
;     ...
;             PG8_LDB(B0, 0, 0); PG8_LDB(B1, 0, 1); PG8_SCHED; PG8_LDA(At, 0, 0); PG8_STAGE(PG8_SA(1, 1), a1 + hstep, voffA);
;             PG8_WAIT_V(8); PG8_WAIT_L(0); PG8_BAR; PG8_MMA(0, 0, At, B0); PG8_MMA(0, 1, At, B1); PG8_BAR; PG8_SCHED;
;             PG8_LDA(At, 0, 1); PG8_STAGE(PG8_SB(0, 0), b2, voffB); PG8_STAGE(PG8_SB(0, 1), b2 + hstep, voffB); PG8_STAGE(PG8_SA(0, 0), a2, voffA);
;             PG8_WAIT_V(8); PG8_WAIT_L(0); PG8_BAR; PG8_MMA(1, 0, At, B0); PG8_MMA(1, 1, At, B1); PG8_BAR; PG8_SCHED;
;             PG8_LDB(B0, 1, 0); PG8_LDB(B1, 1, 1); PG8_SCHED; PG8_LDA(At, 1, 0); PG8_STAGE(PG8_SA(0, 1), a2 + hstep, voffA);
;             PG8_WAIT_V(8); PG8_WAIT_L(0); PG8_BAR; PG8_MMA(0, 0, At, B0); PG8_MMA(0, 1, At, B1); PG8_BAR; PG8_SCHED;
;             PG8_LDA(At, 1, 1); PG8_STAGE(PG8_SB(1, 0), b3, voffB); PG8_STAGE(PG8_SB(1, 1), b3 + hstep, voffB); PG8_STAGE(PG8_SA(1, 0), a3, voffA);
;             PG8_WAIT_V(8); PG8_WAIT_L(0); PG8_BAR; PG8_MMA(1, 0, At, B0); PG8_MMA(1, 1, At, B1); PG8_BAR; PG8_SCHED;
;     ...
;         if constexpr (ALIGN_EPI) { if (wr == 0) PG8_BAR; }
;     __device__ __forceinline__ void operator()(const f32x4 (&acc)[2][2][4][2], const Unit& u, int wr, int wc, int fr, int fq) const {
;         const int row0 = u.pm * BM + wr * 64 + fr, col0 = u.pn * BM + wc * 32 + 8 * fq; const float* gp = gate + (size_t)(u.pm >> 3) * gstride + col0;
;         f32x4 gv[2][2];
; #pragma unroll
;         for (int bj = 0; bj < 2; ++bj)
; #pragma unroll
;             for (int n = 0; n < 2; ++n) gv[bj][n] = *(const f32x4*)(gp + bj * HALF + 4 * n);
; #pragma unroll
;         for (int ai = 0; ai < 2; ++ai)
; #pragma unroll
;             for (int m = 0; m < 4; ++m) { const size_t off = (size_t)(row0 + ai * HALF + m * 16) * ldc + col0;
; #pragma unroll
;                 for (int bj = 0; bj < 2; ++bj) { const u32x4 bw = *(const u32x4*)(base + off + bj * HALF);
	s_add_i32 s26, s54, s29
	v_lshl_add_u64 v[162:163], v[162:163], 0, s[84:85]
	s_mov_b32 m0, s26
	ds_read_b128 v[182:185], v169 offset:49152
	ds_read_b128 v[186:189], v169 offset:50176
	ds_read_b128 v[190:193], v169 offset:51200
	ds_read_b128 v[194:197], v169 offset:52224
	ds_read_b128 v[198:201], v169 offset:53248
	ds_read_b128 v[202:205], v169 offset:54272
	ds_read_b128 v[206:209], v169 offset:55296
	ds_read_b128 v[210:213], v169 offset:56320
	global_load_lds_dwordx4 v[162:163], off
	v_lshl_add_u64 v[162:163], v[218:219], 0, s[84:85]
	s_add_i32 m0, s26, 0x2000
	s_add_i32 s26, s55, s29
	global_load_lds_dwordx4 v[162:163], off
	v_lshl_add_u64 v[162:163], v[220:221], 0, s[84:85]
	s_mov_b32 m0, s26
	s_nop 0
	global_load_lds_dwordx4 v[162:163], off
	v_lshl_add_u64 v[162:163], v[226:227], 0, s[84:85]
	s_add_i32 m0, s26, 0x2000
	s_nop 0
	global_load_lds_dwordx4 v[162:163], off
	v_lshl_add_u64 v[162:163], v[228:229], 0, s[84:85]
	s_mov_b32 m0, s40
	s_nop 0
	global_load_lds_dwordx4 v[162:163], off
	v_lshl_add_u64 v[162:163], v[230:231], 0, s[84:85]
	s_mov_b32 m0, s41
	s_nop 0
	global_load_lds_dwordx4 v[162:163], off
	s_waitcnt vmcnt(8)
	s_waitcnt lgkmcnt(0)
	s_barrier
	s_setprio 1
	s_waitcnt lgkmcnt(0)
	v_mfma_f32_16x16x32_bf16 v[62:65], v[106:109], v[182:185], v[62:65]
	v_mfma_f32_16x16x32_bf16 v[58:61], v[130:133], v[182:185], v[58:61]
	v_mfma_f32_16x16x32_bf16 v[46:49], v[106:109], v[190:193], v[46:49]
	v_mfma_f32_16x16x32_bf16 v[42:45], v[130:133], v[190:193], v[42:45]
	v_mfma_f32_16x16x32_bf16 v[30:33], v[106:109], v[198:201], v[30:33]
	v_mfma_f32_16x16x32_bf16 v[26:29], v[130:133], v[198:201], v[26:29]
	v_mfma_f32_16x16x32_bf16 v[14:17], v[106:109], v[206:209], v[14:17]
	v_mfma_f32_16x16x32_bf16 v[10:13], v[130:133], v[206:209], v[10:13]
	v_mfma_f32_16x16x32_bf16 v[62:65], v[110:113], v[186:189], v[62:65]
	v_mfma_f32_16x16x32_bf16 v[58:61], v[134:137], v[186:189], v[58:61]
	v_mfma_f32_16x16x32_bf16 v[46:49], v[110:113], v[194:197], v[46:49]
	v_mfma_f32_16x16x32_bf16 v[42:45], v[134:137], v[194:197], v[42:45]
	v_mfma_f32_16x16x32_bf16 v[30:33], v[110:113], v[202:205], v[30:33]
	v_mfma_f32_16x16x32_bf16 v[26:29], v[134:137], v[202:205], v[26:29]
	v_mfma_f32_16x16x32_bf16 v[14:17], v[110:113], v[210:213], v[14:17]
	v_mfma_f32_16x16x32_bf16 v[10:13], v[134:137], v[210:213], v[10:13]
	s_setprio 0
	s_setprio 1
	v_mfma_f32_16x16x32_bf16 v[54:57], v[158:161], v[182:185], v[54:57]
	v_mfma_f32_16x16x32_bf16 v[50:53], v[174:177], v[182:185], v[50:53]
	v_mfma_f32_16x16x32_bf16 v[38:41], v[158:161], v[190:193], v[38:41]
	v_mfma_f32_16x16x32_bf16 v[34:37], v[174:177], v[190:193], v[34:37]
	v_mfma_f32_16x16x32_bf16 v[22:25], v[158:161], v[198:201], v[22:25]
	v_mfma_f32_16x16x32_bf16 v[18:21], v[174:177], v[198:201], v[18:21]
	v_mfma_f32_16x16x32_bf16 v[6:9], v[158:161], v[206:209], v[6:9]
	v_mfma_f32_16x16x32_bf16 v[2:5], v[174:177], v[206:209], v[2:5]
	v_mfma_f32_16x16x32_bf16 v[54:57], v[170:173], v[186:189], v[54:57]
	v_mfma_f32_16x16x32_bf16 v[50:53], v[178:181], v[186:189], v[50:53]
	v_mfma_f32_16x16x32_bf16 v[38:41], v[170:173], v[194:197], v[38:41]
	v_mfma_f32_16x16x32_bf16 v[34:37], v[178:181], v[194:197], v[34:37]
	v_mfma_f32_16x16x32_bf16 v[22:25], v[170:173], v[202:205], v[22:25]
	v_mfma_f32_16x16x32_bf16 v[18:21], v[178:181], v[202:205], v[18:21]
	v_mfma_f32_16x16x32_bf16 v[6:9], v[170:173], v[210:213], v[6:9]
	v_mfma_f32_16x16x32_bf16 v[2:5], v[178:181], v[210:213], v[2:5]
	s_setprio 0
	s_barrier
	s_add_u32 s24, s24, 0x100
	s_addc_u32 s25, s25, 0
	s_add_u32 s47, s47, 0x100
	s_addc_u32 s51, s51, 0
	s_cmp_ge_u32 s52, s39
	s_mov_b32 s26, s52
	s_cbranch_scc0 .LBB0_179
	v_lshl_add_u32 v162, s45, 8, v1
	v_lshl_or_b32 v160, s46, 8, v168
	v_ashrrev_i32_e32 v163, 31, v162
	v_ashrrev_i32_e32 v161, 31, v160
	v_lshlrev_b64 v[106:107], 11, v[162:163]
	v_lshl_add_u64 v[106:107], v[106:107], 0, v[160:161]
	v_lshlrev_b64 v[158:159], 1, v[106:107]
	s_ashr_i32 s24, s45, 3
	v_lshl_add_u64 v[174:175], s[10:11], 0, v[158:159]
	s_mul_hi_i32 s25, s24, 0xc000
	s_mul_i32 s24, s24, 0xc000
	global_load_dwordx4 v[170:173], v[174:175], off
	s_add_u32 s24, s37, s24
	s_addc_u32 s25, s38, s25
	v_lshl_add_u64 v[110:111], v[160:161], 2, s[24:25]
	global_load_dwordx4 v[134:137], v[110:111], off
	global_load_dwordx4 v[130:133], v[110:111], off offset:16
	global_load_dwordx4 v[106:109], v[110:111], off offset:528
	s_nop 0
	global_load_dwordx4 v[110:113], v[110:111], off offset:512
	global_load_dwordx4 v[182:185], v[174:175], off offset:256
	s_mov_b64 s[24:25], 0x10000
	v_lshl_add_u64 v[218:219], v[174:175], 0, s[24:25]
	global_load_dwordx4 v[186:189], v[218:219], off
	global_load_dwordx4 v[190:193], v[218:219], off offset:256
	s_mov_b64 s[24:25], 0x20000
	v_lshl_add_u64 v[218:219], v[174:175], 0, s[24:25]
	global_load_dwordx4 v[194:197], v[218:219], off
	global_load_dwordx4 v[198:201], v[218:219], off offset:256
	s_mov_b64 s[24:25], 0x30000
	v_lshl_add_u64 v[218:219], v[174:175], 0, s[24:25]
	global_load_dwordx4 v[202:205], v[218:219], off
	global_load_dwordx4 v[206:209], v[218:219], off offset:256
	s_mov_b64 s[24:25], 0x80000
	v_lshl_add_u64 v[218:219], v[174:175], 0, s[24:25]
	global_load_dwordx4 v[210:213], v[218:219], off
	global_load_dwordx4 v[226:229], v[218:219], off offset:256
	s_mov_b64 s[24:25], 0x90000
	v_lshl_add_u64 v[218:219], v[174:175], 0, s[24:25]
	global_load_dwordx4 v[230:233], v[218:219], off
	global_load_dwordx4 v[234:237], v[218:219], off offset:256
	s_mov_b64 s[24:25], 0xa0000
	v_lshl_add_u64 v[218:219], v[174:175], 0, s[24:25]
	global_load_dwordx4 v[238:241], v[218:219], off
	global_load_dwordx4 v[242:245], v[218:219], off offset:256
	s_mov_b64 s[24:25], 0xb0000
	v_lshl_add_u64 v[218:219], v[174:175], 0, s[24:25]
	global_load_dwordx4 v[246:249], v[218:219], off
	global_load_dwordx4 v[250:253], v[218:219], off offset:256
	v_lshl_add_u64 v[176:177], s[16:17], 0, v[158:159]
	s_mov_b64 s[24:25], 0x80000
	s_and_b64 vcc, exec, s[20:21]
	s_cbranch_vccz .LBB0_182
	s_barrier
; __device__ __forceinline__ unsigned cvt_pk_bf16(float lo, float hi) { unsigned r; asm volatile("v_cvt_pk_bf16_f32 %0, %1, %2" : "=v"(r) : "v"(lo), "v"(hi)); return r; }
;     __device__ __forceinline__ void operator()(const f32x4 (&acc)[2][2][4][2], const Unit& u, int wr, int wc, int fr, int fq) const {
;     ...
;             for (int m = 0; m < 4; ++m) { const size_t off = (size_t)(row0 + ai * HALF + m * 16) * ldc + col0;
; #pragma unroll
;                 for (int bj = 0; bj < 2; ++bj) { const u32x4 bw = *(const u32x4*)(base + off + bj * HALF);
;                     const f32x4 a0 = acc[ai][bj][m][0], a1 = acc[ai][bj][m][1], g0 = gv[bj][0], g1 = gv[bj][1];
;                     u32x4 w;
;                     w.x = cvt_pk_bf16(__uint_as_float(bw.x << 16) + g0[0] * a0[0], __uint_as_float(bw.x & 0xffff0000u) + g0[1] * a0[1]);
;                     w.y = cvt_pk_bf16(__uint_as_float(bw.y << 16) + g0[2] * a0[2], __uint_as_float(bw.y & 0xffff0000u) + g0[3] * a0[3]);
;                     w.z = cvt_pk_bf16(__uint_as_float(bw.z << 16) + g1[0] * a1[0], __uint_as_float(bw.z & 0xffff0000u) + g1[1] * a1[1]);
;                     w.w = cvt_pk_bf16(__uint_as_float(bw.w << 16) + g1[2] * a1[2], __uint_as_float(bw.w & 0xffff0000u) + g1[3] * a1[3]);
;                     *(u32x4*)(out + off + bj * HALF) = w; } }
.LBB0_182:
	s_and_b64 vcc, exec, s[6:7]
	s_mov_b64 s[6:7], -1
	s_waitcnt vmcnt(15)
	v_lshlrev_b32_e32 v163, 16, v170
	v_and_b32_e32 v170, 0xffff0000, v170
	v_lshlrev_b32_e32 v178, 16, v171
	v_and_b32_e32 v171, 0xffff0000, v171
	v_lshlrev_b32_e32 v179, 16, v172
	v_and_b32_e32 v172, 0xffff0000, v172
	v_lshlrev_b32_e32 v180, 16, v173
	v_and_b32_e32 v173, 0xffff0000, v173
	v_fmac_f32_e32 v163, v142, v134
	v_fmac_f32_e32 v170, v143, v135
	v_fmac_f32_e32 v178, v144, v136
	v_fmac_f32_e32 v171, v145, v137
	v_fmac_f32_e32 v179, v138, v130
	v_fmac_f32_e32 v172, v139, v131
	v_fmac_f32_e32 v180, v140, v132
	v_fmac_f32_e32 v173, v141, v133
	v_cvt_pk_bf16_f32 v138, v163, v170
	v_cvt_pk_bf16_f32 v139, v178, v171
	v_cvt_pk_bf16_f32 v140, v179, v172
	v_cvt_pk_bf16_f32 v141, v180, v173
	global_store_dwordx4 v[176:177], v[138:141], off
	v_or_b32_e32 v142, 16, v162
	v_ashrrev_i32_e32 v143, 31, v142
	v_lshlrev_b64 v[142:143], 11, v[142:143]
	v_lshl_add_u64 v[142:143], v[142:143], 0, v[160:161]
	v_lshlrev_b64 v[142:143], 1, v[142:143]
	v_lshl_add_u64 v[144:145], s[10:11], 0, v[142:143]
	s_waitcnt vmcnt(15)
	v_lshlrev_b32_e32 v163, 16, v182
	v_and_b32_e32 v138, 0xffff0000, v182
	v_lshlrev_b32_e32 v170, 16, v183
	v_and_b32_e32 v139, 0xffff0000, v183
	v_lshlrev_b32_e32 v171, 16, v184
	v_and_b32_e32 v140, 0xffff0000, v184
	v_lshlrev_b32_e32 v172, 16, v185
	v_and_b32_e32 v141, 0xffff0000, v185
	v_fmac_f32_e32 v163, v126, v110
	v_fmac_f32_e32 v138, v127, v111
	v_fmac_f32_e32 v170, v128, v112
	v_fmac_f32_e32 v139, v129, v113
	v_fmac_f32_e32 v171, v122, v106
	v_fmac_f32_e32 v140, v123, v107
	v_fmac_f32_e32 v172, v124, v108
	v_fmac_f32_e32 v141, v125, v109
	v_cvt_pk_bf16_f32 v122, v163, v138
	v_cvt_pk_bf16_f32 v123, v170, v139
	v_cvt_pk_bf16_f32 v124, v171, v140
	v_cvt_pk_bf16_f32 v125, v172, v141
	global_store_dwordx4 v[176:177], v[122:125], off offset:256
	v_lshl_add_u64 v[126:127], s[16:17], 0, v[142:143]
	s_waitcnt vmcnt(15)
	v_lshlrev_b32_e32 v128, 16, v186
	v_and_b32_e32 v122, 0xffff0000, v186
	v_lshlrev_b32_e32 v129, 16, v187
	v_and_b32_e32 v123, 0xffff0000, v187
	v_lshlrev_b32_e32 v138, 16, v188
	v_and_b32_e32 v124, 0xffff0000, v188
	v_lshlrev_b32_e32 v139, 16, v189
	v_and_b32_e32 v125, 0xffff0000, v189
	v_fmac_f32_e32 v128, v118, v134
	v_fmac_f32_e32 v122, v119, v135
	v_fmac_f32_e32 v129, v120, v136
	v_fmac_f32_e32 v123, v121, v137
	v_fmac_f32_e32 v138, v114, v130
	v_fmac_f32_e32 v124, v115, v131
	v_fmac_f32_e32 v139, v116, v132
	v_fmac_f32_e32 v125, v117, v133
	v_cvt_pk_bf16_f32 v114, v128, v122
	v_cvt_pk_bf16_f32 v115, v129, v123
	v_cvt_pk_bf16_f32 v116, v138, v124
	v_cvt_pk_bf16_f32 v117, v139, v125
	global_store_dwordx4 v[126:127], v[114:117], off
	v_or_b32_e32 v118, 32, v162
	v_ashrrev_i32_e32 v119, 31, v118
	v_lshlrev_b64 v[118:119], 11, v[118:119]
	v_lshl_add_u64 v[118:119], v[118:119], 0, v[160:161]
	v_lshlrev_b64 v[118:119], 1, v[118:119]
	v_lshl_add_u64 v[120:121], s[10:11], 0, v[118:119]
	s_waitcnt vmcnt(15)
	v_lshlrev_b32_e32 v122, 16, v190
	v_and_b32_e32 v114, 0xffff0000, v190
	v_lshlrev_b32_e32 v123, 16, v191
	v_and_b32_e32 v115, 0xffff0000, v191
	v_lshlrev_b32_e32 v124, 16, v192
	v_and_b32_e32 v116, 0xffff0000, v192
	v_lshlrev_b32_e32 v125, 16, v193
	v_and_b32_e32 v117, 0xffff0000, v193
	v_fmac_f32_e32 v122, v102, v110
	v_fmac_f32_e32 v114, v103, v111
	v_fmac_f32_e32 v123, v104, v112
	v_fmac_f32_e32 v115, v105, v113
	v_fmac_f32_e32 v124, v98, v106
	v_fmac_f32_e32 v116, v99, v107
	v_fmac_f32_e32 v125, v100, v108
	v_fmac_f32_e32 v117, v101, v109
	v_cvt_pk_bf16_f32 v98, v122, v114
	v_cvt_pk_bf16_f32 v99, v123, v115
	v_cvt_pk_bf16_f32 v100, v124, v116
	v_cvt_pk_bf16_f32 v101, v125, v117
	global_store_dwordx4 v[126:127], v[98:101], off offset:256
	v_lshl_add_u64 v[102:103], s[16:17], 0, v[118:119]
	s_waitcnt vmcnt(15)
	v_lshlrev_b32_e32 v104, 16, v194
	v_and_b32_e32 v98, 0xffff0000, v194
	v_lshlrev_b32_e32 v105, 16, v195
	v_and_b32_e32 v99, 0xffff0000, v195
	v_lshlrev_b32_e32 v114, 16, v196
	v_and_b32_e32 v100, 0xffff0000, v196
	v_lshlrev_b32_e32 v115, 16, v197
	v_and_b32_e32 v101, 0xffff0000, v197
	v_fmac_f32_e32 v104, v94, v134
	v_fmac_f32_e32 v98, v95, v135
	v_fmac_f32_e32 v105, v96, v136
	v_fmac_f32_e32 v99, v97, v137
	v_fmac_f32_e32 v114, v90, v130
	v_fmac_f32_e32 v100, v91, v131
	v_fmac_f32_e32 v115, v92, v132
	v_fmac_f32_e32 v101, v93, v133
	v_cvt_pk_bf16_f32 v90, v104, v98
	v_cvt_pk_bf16_f32 v91, v105, v99
	v_cvt_pk_bf16_f32 v92, v114, v100
	v_cvt_pk_bf16_f32 v93, v115, v101
	global_store_dwordx4 v[102:103], v[90:93], off
	v_or_b32_e32 v94, 48, v162
	v_ashrrev_i32_e32 v95, 31, v94
	v_lshlrev_b64 v[94:95], 11, v[94:95]
	v_lshl_add_u64 v[94:95], v[94:95], 0, v[160:161]
	v_lshlrev_b64 v[94:95], 1, v[94:95]
	v_lshl_add_u64 v[96:97], s[10:11], 0, v[94:95]
	s_waitcnt vmcnt(15)
	v_lshlrev_b32_e32 v98, 16, v198
	v_and_b32_e32 v90, 0xffff0000, v198
	v_lshlrev_b32_e32 v99, 16, v199
	v_and_b32_e32 v91, 0xffff0000, v199
	v_lshlrev_b32_e32 v100, 16, v200
	v_and_b32_e32 v92, 0xffff0000, v200
	v_lshlrev_b32_e32 v101, 16, v201
	v_and_b32_e32 v93, 0xffff0000, v201
	v_fmac_f32_e32 v98, v86, v110
	v_fmac_f32_e32 v90, v87, v111
	v_fmac_f32_e32 v99, v88, v112
	v_fmac_f32_e32 v91, v89, v113
	v_fmac_f32_e32 v100, v82, v106
	v_fmac_f32_e32 v92, v83, v107
	v_fmac_f32_e32 v101, v84, v108
	v_fmac_f32_e32 v93, v85, v109
	v_cvt_pk_bf16_f32 v82, v98, v90
	v_cvt_pk_bf16_f32 v83, v99, v91
	v_cvt_pk_bf16_f32 v84, v100, v92
	v_cvt_pk_bf16_f32 v85, v101, v93
	global_store_dwordx4 v[102:103], v[82:85], off offset:256
	v_lshl_add_u64 v[86:87], s[16:17], 0, v[94:95]
	s_waitcnt vmcnt(15)
; __device__ __forceinline__ unsigned cvt_pk_bf16(float lo, float hi) { unsigned r; asm volatile("v_cvt_pk_bf16_f32 %0, %1, %2" : "=v"(r) : "v"(lo), "v"(hi)); return r; }
;     __device__ __forceinline__ void operator()(const f32x4 (&acc)[2][2][4][2], const Unit& u, int wr, int wc, int fr, int fq) const {
;     ...
;             for (int m = 0; m < 4; ++m) { const size_t off = (size_t)(row0 + ai * HALF + m * 16) * ldc + col0;
; #pragma unroll
;                 for (int bj = 0; bj < 2; ++bj) { const u32x4 bw = *(const u32x4*)(base + off + bj * HALF);
;                     const f32x4 a0 = acc[ai][bj][m][0], a1 = acc[ai][bj][m][1], g0 = gv[bj][0], g1 = gv[bj][1];
;                     u32x4 w;
;                     w.x = cvt_pk_bf16(__uint_as_float(bw.x << 16) + g0[0] * a0[0], __uint_as_float(bw.x & 0xffff0000u) + g0[1] * a0[1]);
;                     w.y = cvt_pk_bf16(__uint_as_float(bw.y << 16) + g0[2] * a0[2], __uint_as_float(bw.y & 0xffff0000u) + g0[3] * a0[3]);
;                     w.z = cvt_pk_bf16(__uint_as_float(bw.z << 16) + g1[0] * a1[0], __uint_as_float(bw.z & 0xffff0000u) + g1[1] * a1[1]);
;                     w.w = cvt_pk_bf16(__uint_as_float(bw.w << 16) + g1[2] * a1[2], __uint_as_float(bw.w & 0xffff0000u) + g1[3] * a1[3]);
;                     *(u32x4*)(out + off + bj * HALF) = w; } }
	v_lshlrev_b32_e32 v88, 16, v202
	v_and_b32_e32 v82, 0xffff0000, v202
	v_lshlrev_b32_e32 v89, 16, v203
	v_and_b32_e32 v83, 0xffff0000, v203
	v_lshlrev_b32_e32 v90, 16, v204
	v_and_b32_e32 v84, 0xffff0000, v204
	v_lshlrev_b32_e32 v91, 16, v205
	v_and_b32_e32 v85, 0xffff0000, v205
	v_fmac_f32_e32 v88, v78, v134
	v_fmac_f32_e32 v82, v79, v135
	v_fmac_f32_e32 v89, v80, v136
	v_fmac_f32_e32 v83, v81, v137
	v_fmac_f32_e32 v90, v74, v130
	v_fmac_f32_e32 v84, v75, v131
	v_fmac_f32_e32 v91, v76, v132
	v_fmac_f32_e32 v85, v77, v133
	v_cvt_pk_bf16_f32 v74, v88, v82
	v_cvt_pk_bf16_f32 v75, v89, v83
	v_cvt_pk_bf16_f32 v76, v90, v84
	v_cvt_pk_bf16_f32 v77, v91, v85
	global_store_dwordx4 v[86:87], v[74:77], off
	v_lshl_add_u64 v[78:79], v[158:159], 0, s[24:25]
	v_lshl_add_u64 v[80:81], s[10:11], 0, v[78:79]
	s_mov_b64 s[24:25], 0x90000
	s_waitcnt vmcnt(15)
	v_lshlrev_b32_e32 v82, 16, v206
	v_and_b32_e32 v74, 0xffff0000, v206
	v_lshlrev_b32_e32 v83, 16, v207
	v_and_b32_e32 v75, 0xffff0000, v207
	v_lshlrev_b32_e32 v84, 16, v208
	v_and_b32_e32 v76, 0xffff0000, v208
	v_lshlrev_b32_e32 v85, 16, v209
	v_and_b32_e32 v77, 0xffff0000, v209
	v_fmac_f32_e32 v82, v70, v110
	v_fmac_f32_e32 v74, v71, v111
	v_fmac_f32_e32 v83, v72, v112
	v_fmac_f32_e32 v75, v73, v113
	v_fmac_f32_e32 v84, v66, v106
	v_fmac_f32_e32 v76, v67, v107
	v_fmac_f32_e32 v85, v68, v108
	v_fmac_f32_e32 v77, v69, v109
	v_cvt_pk_bf16_f32 v66, v82, v74
	v_cvt_pk_bf16_f32 v67, v83, v75
	v_cvt_pk_bf16_f32 v68, v84, v76
	v_cvt_pk_bf16_f32 v69, v85, v77
	global_store_dwordx4 v[86:87], v[66:69], off offset:256
	v_lshl_add_u64 v[70:71], s[16:17], 0, v[78:79]
	s_waitcnt vmcnt(15)
	v_lshlrev_b32_e32 v72, 16, v210
	v_and_b32_e32 v66, 0xffff0000, v210
	v_lshlrev_b32_e32 v73, 16, v211
	v_and_b32_e32 v67, 0xffff0000, v211
	v_lshlrev_b32_e32 v74, 16, v212
	v_and_b32_e32 v68, 0xffff0000, v212
	v_lshlrev_b32_e32 v75, 16, v213
	v_and_b32_e32 v69, 0xffff0000, v213
	v_fmac_f32_e32 v72, v62, v134
	v_fmac_f32_e32 v66, v63, v135
	v_fmac_f32_e32 v73, v64, v136
	v_fmac_f32_e32 v67, v65, v137
	v_fmac_f32_e32 v74, v58, v130
	v_fmac_f32_e32 v68, v59, v131
	v_fmac_f32_e32 v75, v60, v132
	v_fmac_f32_e32 v69, v61, v133
	v_cvt_pk_bf16_f32 v58, v72, v66
	v_cvt_pk_bf16_f32 v59, v73, v67
	v_cvt_pk_bf16_f32 v60, v74, v68
	v_cvt_pk_bf16_f32 v61, v75, v69
	global_store_dwordx4 v[70:71], v[58:61], off
	v_lshl_add_u64 v[62:63], v[158:159], 0, s[24:25]
	v_lshl_add_u64 v[64:65], s[10:11], 0, v[62:63]
	s_mov_b64 s[24:25], 0xa0000
	s_waitcnt vmcnt(15)
	v_lshlrev_b32_e32 v66, 16, v226
	v_and_b32_e32 v58, 0xffff0000, v226
	v_lshlrev_b32_e32 v67, 16, v227
	v_and_b32_e32 v59, 0xffff0000, v227
	v_lshlrev_b32_e32 v68, 16, v228
	v_and_b32_e32 v60, 0xffff0000, v228
	v_lshlrev_b32_e32 v69, 16, v229
	v_and_b32_e32 v61, 0xffff0000, v229
	v_fmac_f32_e32 v66, v54, v110
	v_fmac_f32_e32 v58, v55, v111
	v_fmac_f32_e32 v67, v56, v112
	v_fmac_f32_e32 v59, v57, v113
	v_fmac_f32_e32 v68, v50, v106
	v_fmac_f32_e32 v60, v51, v107
	v_fmac_f32_e32 v69, v52, v108
	v_fmac_f32_e32 v61, v53, v109
	v_cvt_pk_bf16_f32 v50, v66, v58
	v_cvt_pk_bf16_f32 v51, v67, v59
	v_cvt_pk_bf16_f32 v52, v68, v60
	v_cvt_pk_bf16_f32 v53, v69, v61
	global_store_dwordx4 v[70:71], v[50:53], off offset:256
	v_lshl_add_u64 v[54:55], s[16:17], 0, v[62:63]
	s_waitcnt vmcnt(15)
	v_lshlrev_b32_e32 v56, 16, v230
	v_and_b32_e32 v50, 0xffff0000, v230
	v_lshlrev_b32_e32 v57, 16, v231
	v_and_b32_e32 v51, 0xffff0000, v231
	v_lshlrev_b32_e32 v58, 16, v232
	v_and_b32_e32 v52, 0xffff0000, v232
	v_lshlrev_b32_e32 v59, 16, v233
	v_and_b32_e32 v53, 0xffff0000, v233
	v_fmac_f32_e32 v56, v46, v134
	v_fmac_f32_e32 v50, v47, v135
	v_fmac_f32_e32 v57, v48, v136
	v_fmac_f32_e32 v51, v49, v137
	v_fmac_f32_e32 v58, v42, v130
	v_fmac_f32_e32 v52, v43, v131
	v_fmac_f32_e32 v59, v44, v132
	v_fmac_f32_e32 v53, v45, v133
	v_cvt_pk_bf16_f32 v42, v56, v50
	v_cvt_pk_bf16_f32 v43, v57, v51
	v_cvt_pk_bf16_f32 v44, v58, v52
	v_cvt_pk_bf16_f32 v45, v59, v53
	global_store_dwordx4 v[54:55], v[42:45], off
	v_lshl_add_u64 v[46:47], v[158:159], 0, s[24:25]
	v_lshl_add_u64 v[48:49], s[10:11], 0, v[46:47]
	s_mov_b64 s[24:25], 0xb0000
	s_waitcnt vmcnt(15)
; __device__ __forceinline__ unsigned cvt_pk_bf16(float lo, float hi) { unsigned r; asm volatile("v_cvt_pk_bf16_f32 %0, %1, %2" : "=v"(r) : "v"(lo), "v"(hi)); return r; }
; #define PG8_BAR __builtin_amdgcn_s_barrier()
; template <class Epi, class Sched, bool ALIGN_EPI = false, bool SP2 = false>
; __device__ __forceinline__ void gemm_phase(PG8_LAS unsigned char* lds, const Gemm g, const Sched& S, const Epi& E) {
;     ...
;         if (!has_next) break;
; #pragma unroll
;         for (int a = 0; a < 2; ++a)
; #pragma unroll
;             for (int b = 0; b < 2; ++b)
; #pragma unroll
;                 for (int m = 0; m < 4; ++m)
; #pragma unroll
;                     for (int n = 0; n < 2; ++n) acc[a][b][m][n] = (f32x4){0.f, 0.f, 0.f, 0.f};
;         cur = nxt; cA = nA; cB = nB; ++ui;
;         if constexpr (ALIGN_EPI) { if (wr == 1) PG8_BAR; }
;     __device__ __forceinline__ void operator()(const f32x4 (&acc)[2][2][4][2], const Unit& u, int wr, int wc, int fr, int fq) const {
;     ...
;             for (int m = 0; m < 4; ++m) { const size_t off = (size_t)(row0 + ai * HALF + m * 16) * ldc + col0;
; #pragma unroll
;                 for (int bj = 0; bj < 2; ++bj) { const u32x4 bw = *(const u32x4*)(base + off + bj * HALF);
;                     const f32x4 a0 = acc[ai][bj][m][0], a1 = acc[ai][bj][m][1], g0 = gv[bj][0], g1 = gv[bj][1];
;                     u32x4 w;
;                     w.x = cvt_pk_bf16(__uint_as_float(bw.x << 16) + g0[0] * a0[0], __uint_as_float(bw.x & 0xffff0000u) + g0[1] * a0[1]);
;                     w.y = cvt_pk_bf16(__uint_as_float(bw.y << 16) + g0[2] * a0[2], __uint_as_float(bw.y & 0xffff0000u) + g0[3] * a0[3]);
;                     w.z = cvt_pk_bf16(__uint_as_float(bw.z << 16) + g1[0] * a1[0], __uint_as_float(bw.z & 0xffff0000u) + g1[1] * a1[1]);
;                     w.w = cvt_pk_bf16(__uint_as_float(bw.w << 16) + g1[2] * a1[2], __uint_as_float(bw.w & 0xffff0000u) + g1[3] * a1[3]);
;                     *(u32x4*)(out + off + bj * HALF) = w; } }
	v_lshlrev_b32_e32 v50, 16, v234
	v_and_b32_e32 v42, 0xffff0000, v234
	v_lshlrev_b32_e32 v51, 16, v235
	v_and_b32_e32 v43, 0xffff0000, v235
	v_lshlrev_b32_e32 v52, 16, v236
	v_and_b32_e32 v44, 0xffff0000, v236
	v_lshlrev_b32_e32 v53, 16, v237
	v_and_b32_e32 v45, 0xffff0000, v237
	v_fmac_f32_e32 v50, v38, v110
	v_fmac_f32_e32 v42, v39, v111
	v_fmac_f32_e32 v51, v40, v112
	v_fmac_f32_e32 v43, v41, v113
	v_fmac_f32_e32 v52, v34, v106
	v_fmac_f32_e32 v44, v35, v107
	v_fmac_f32_e32 v53, v36, v108
	v_fmac_f32_e32 v45, v37, v109
	v_cvt_pk_bf16_f32 v34, v50, v42
	v_cvt_pk_bf16_f32 v35, v51, v43
	v_cvt_pk_bf16_f32 v36, v52, v44
	v_cvt_pk_bf16_f32 v37, v53, v45
	global_store_dwordx4 v[54:55], v[34:37], off offset:256
	v_lshl_add_u64 v[38:39], s[16:17], 0, v[46:47]
	s_waitcnt vmcnt(15)
	v_lshlrev_b32_e32 v40, 16, v238
	v_and_b32_e32 v34, 0xffff0000, v238
	v_lshlrev_b32_e32 v41, 16, v239
	v_and_b32_e32 v35, 0xffff0000, v239
	v_lshlrev_b32_e32 v42, 16, v240
	v_and_b32_e32 v36, 0xffff0000, v240
	v_lshlrev_b32_e32 v43, 16, v241
	v_and_b32_e32 v37, 0xffff0000, v241
	v_fmac_f32_e32 v40, v30, v134
	v_fmac_f32_e32 v34, v31, v135
	v_fmac_f32_e32 v41, v32, v136
	v_fmac_f32_e32 v35, v33, v137
	v_fmac_f32_e32 v42, v26, v130
	v_fmac_f32_e32 v36, v27, v131
	v_fmac_f32_e32 v43, v28, v132
	v_fmac_f32_e32 v37, v29, v133
	v_cvt_pk_bf16_f32 v26, v40, v34
	v_cvt_pk_bf16_f32 v27, v41, v35
	v_cvt_pk_bf16_f32 v28, v42, v36
	v_cvt_pk_bf16_f32 v29, v43, v37
	global_store_dwordx4 v[38:39], v[26:29], off
	v_lshl_add_u64 v[30:31], v[158:159], 0, s[24:25]
	v_lshl_add_u64 v[32:33], s[10:11], 0, v[30:31]
	s_waitcnt vmcnt(15)
	v_lshlrev_b32_e32 v34, 16, v242
	v_and_b32_e32 v26, 0xffff0000, v242
	v_lshlrev_b32_e32 v35, 16, v243
	v_and_b32_e32 v27, 0xffff0000, v243
	v_lshlrev_b32_e32 v36, 16, v244
	v_and_b32_e32 v28, 0xffff0000, v244
	v_lshlrev_b32_e32 v37, 16, v245
	v_and_b32_e32 v29, 0xffff0000, v245
	v_fmac_f32_e32 v34, v22, v110
	v_fmac_f32_e32 v26, v23, v111
	v_fmac_f32_e32 v35, v24, v112
	v_fmac_f32_e32 v27, v25, v113
	v_fmac_f32_e32 v36, v18, v106
	v_fmac_f32_e32 v28, v19, v107
	v_fmac_f32_e32 v37, v20, v108
	v_fmac_f32_e32 v29, v21, v109
	v_cvt_pk_bf16_f32 v18, v34, v26
	v_cvt_pk_bf16_f32 v19, v35, v27
	v_cvt_pk_bf16_f32 v20, v36, v28
	v_cvt_pk_bf16_f32 v21, v37, v29
	global_store_dwordx4 v[38:39], v[18:21], off offset:256
	v_lshl_add_u64 v[22:23], s[16:17], 0, v[30:31]
	s_waitcnt vmcnt(15)
	v_lshlrev_b32_e32 v24, 16, v246
	v_and_b32_e32 v18, 0xffff0000, v246
	v_lshlrev_b32_e32 v25, 16, v247
	v_and_b32_e32 v19, 0xffff0000, v247
	v_lshlrev_b32_e32 v26, 16, v248
	v_and_b32_e32 v20, 0xffff0000, v248
	v_lshlrev_b32_e32 v27, 16, v249
	v_and_b32_e32 v21, 0xffff0000, v249
	v_fmac_f32_e32 v24, v14, v134
	v_fmac_f32_e32 v18, v15, v135
	v_fmac_f32_e32 v25, v16, v136
	v_fmac_f32_e32 v19, v17, v137
	v_fmac_f32_e32 v26, v10, v130
	v_fmac_f32_e32 v20, v11, v131
	v_fmac_f32_e32 v27, v12, v132
	v_fmac_f32_e32 v21, v13, v133
	v_cvt_pk_bf16_f32 v10, v24, v18
	v_cvt_pk_bf16_f32 v11, v25, v19
	v_cvt_pk_bf16_f32 v12, v26, v20
	v_cvt_pk_bf16_f32 v13, v27, v21
	global_store_dwordx4 v[22:23], v[10:13], off
	s_waitcnt vmcnt(15)
	v_lshlrev_b32_e32 v14, 16, v250
	v_and_b32_e32 v10, 0xffff0000, v250
	v_lshlrev_b32_e32 v15, 16, v251
	v_and_b32_e32 v11, 0xffff0000, v251
	v_lshlrev_b32_e32 v16, 16, v252
	v_and_b32_e32 v12, 0xffff0000, v252
	v_lshlrev_b32_e32 v17, 16, v253
	v_and_b32_e32 v13, 0xffff0000, v253
	v_fmac_f32_e32 v14, v6, v110
	v_fmac_f32_e32 v10, v7, v111
	v_fmac_f32_e32 v15, v8, v112
	v_fmac_f32_e32 v11, v9, v113
	v_fmac_f32_e32 v16, v2, v106
	v_fmac_f32_e32 v12, v3, v107
	v_fmac_f32_e32 v17, v4, v108
	v_fmac_f32_e32 v13, v5, v109
	v_cvt_pk_bf16_f32 v2, v14, v10
	v_cvt_pk_bf16_f32 v3, v15, v11
	v_cvt_pk_bf16_f32 v4, v16, v12
	v_cvt_pk_bf16_f32 v5, v17, v13
	global_store_dwordx4 v[22:23], v[2:5], off offset:256
	s_cbranch_vccnz .LBB0_167
	s_andn2_b64 vcc, exec, s[18:19]
	s_cbranch_vccnz .LBB0_166
	s_barrier
	s_branch .LBB0_166
